# v056-tail-piece-remap-XCD-local-A-slices
# speedup vs baseline: 1.0055x; 1.0045x over previous
;     __host__ __device__ bool next(int i, Unit& u) const {
;         const long L = (long)i * G + c;
;         if (L < 256) {
;             const int xcd = (int)L % NXCD, off = (int)L / NXCD;
;             u.pm = xcd * 4 + (off & 3); u.pn = off >> 2; u.k0 = 0; u.nk = nkf; u.part = -1; return true;
;         }
;         const long p = L - 256 - poff; if (p < 0 || p >= 8 * nsl) return false;
;         const int sl = (int)p / 8, pairs = nkf / 2, base = pairs / nsl, rem = pairs % nsl;
;         u.pm = 32; u.pn = (int)p % 8; u.k0 = 2 * (sl * base + (sl < rem ? sl : rem)); u.nk = 2 * (base + (sl < rem ? 1 : 0)); u.part = sl; return true;
.LBB0_338:
	s_cmp_lt_i32 s66, 3
	s_cselect_b64 s[6:7], -1, 0
	s_add_u32 s2, s90, 0x2b40000
	v_writelane_b32 v251, s2, 61
	s_addc_u32 s2, s91, 0
	s_and_b64 s[18:19], s[6:7], s[0:1]
	s_andn2_b64 vcc, exec, s[18:19]
	v_writelane_b32 v251, s2, 62
	s_cbranch_vccnz .LBB0_387
	s_cmpk_gt_i32 s33, 0xff
	v_readfirstlane_b32 s24, v203
	s_cbranch_scc0 .LBB0_342
	s_add_i32 s1, s33, 0xffffff00
	s_cmpk_gt_u32 s1, 0xff
	s_mov_b64 s[22:23], 0
	s_cbranch_scc1 .LBB0_399
	s_and_b32 s20, s1, 31
	s_min_u32 s0, s20, 11
	s_add_i32 s0, s0, s20
	s_lshr_b32 s53, s1, 5
	s_lshl_b32 s0, s0, 16
	s_cmpk_lt_u32 s20, 11
	s_cselect_b32 s54, 4, 2
	s_mov_b32 s1, 0
	s_mov_b32 s52, 32
	s_mov_b64 s[6:7], -1
	s_andn2_b64 vcc, exec, s[22:23]
	s_cbranch_vccz .LBB0_343
	s_branch .LBB0_344

;     __host__ __device__ bool next(int i, Unit& u) const {
;         const long L = (long)i * G + c;
;         if (L < 256) {
;             const int xcd = (int)L % NXCD, off = (int)L / NXCD;
;             u.pm = xcd * 4 + (off & 3); u.pn = off >> 2; u.k0 = 0; u.nk = nkf; u.part = -1; return true;
;         }
;         const long p = L - 256 - poff; if (p < 0 || p >= 8 * nsl) return false;
;         const int sl = (int)p / 8, pairs = nkf / 2, base = pairs / nsl, rem = pairs % nsl;
;         u.pm = 32; u.pn = (int)p % 8; u.k0 = 2 * (sl * base + (sl < rem ? sl : rem)); u.nk = 2 * (base + (sl < rem ? 1 : 0)); u.part = sl; return true;
.LBB0_350:
	s_add_i32 s47, s47, 1
	s_mul_i32 s0, s47, s43
	s_mul_hi_u32 s1, s47, s3
	s_add_i32 s1, s1, s0
	s_mul_i32 s0, s47, s3
	s_add_u32 s0, s0, s33
	s_addc_u32 s1, s1, s11
	v_cmp_gt_i64_e32 vcc, s[0:1], v[136:137]
	s_mov_b64 s[30:31], -1
	s_cbranch_vccz .LBB0_353
	s_add_u32 s38, s0, 0xffffff00
	s_addc_u32 s39, s1, -1
	v_cmp_gt_u64_e32 vcc, s[38:39], v[136:137]
	s_mov_b64 s[30:31], 0
	s_mov_b64 s[28:29], 0
	s_cbranch_vccnz .LBB0_353
	s_and_b32 s48, s38, 31
	s_min_u32 s1, s48, 11
	s_add_i32 s1, s1, s48
	s_lshr_b32 s49, s38, 5
	v_cmp_lt_u64_e32 vcc, s[38:39], v[138:139]
	s_lshl_b32 s26, s1, 1
	s_cmp_lt_u32 s48, 11
	s_cselect_b32 s50, 4, 2
	s_mov_b32 s51, 32
	s_mov_b64 s[28:29], -1

;     __host__ __device__ bool next(int i, Unit& u) const {
;         const long L = (long)i * G + c;
;         if (L < 256) {
;             const int xcd = (int)L % NXCD, off = (int)L / NXCD;
;             u.pm = xcd * 4 + (off & 3); u.pn = off >> 2; u.k0 = 0; u.nk = nkf; u.part = -1; return true;
;         }
;         const long p = L - 256 - poff; if (p < 0 || p >= 8 * nsl) return false;
;         const int sl = (int)p / 8, pairs = nkf / 2, base = pairs / nsl, rem = pairs % nsl;
;         u.pm = 32; u.pn = (int)p % 8; u.k0 = 2 * (sl * base + (sl < rem ? sl : rem)); u.nk = 2 * (base + (sl < rem ? 1 : 0)); u.part = sl; return true;
.LBB0_932:
	s_add_i32 s64, s64, 1
	s_mul_i32 s1, s64, s13
	s_mul_hi_u32 s31, s64, s3
	s_add_i32 s31, s31, s1
	s_mul_i32 s1, s64, s3
	s_add_u32 s40, s1, s33
	s_addc_u32 s41, s31, s11
	v_cmp_gt_i64_e32 vcc, s[40:41], v[216:217]
	s_mov_b64 s[42:43], -1
	s_cbranch_vccz .LBB0_935
	s_sub_u32 s1, s40, s15
	s_subb_u32 s31, s41, 0
	s_add_u32 s50, s1, 0xffffff00
	s_addc_u32 s51, s31, -1
	v_cmp_gt_u64_e64 s[38:39], s[50:51], 63
	s_mov_b64 s[42:43], 0
	s_and_b64 vcc, exec, s[38:39]
	s_mov_b64 s[38:39], 0
	s_cbranch_vccnz .LBB0_935
	s_and_b32 s65, s50, 7
	s_lshl_b32 s30, s65, 1
	s_lshr_b32 s34, s50, 3
	s_mov_b32 s66, 2
	s_mov_b32 s36, 32
	s_mov_b64 s[38:39], -1

;     __host__ __device__ bool next(int i, Unit& u) const {
;         const long L = (long)i * G + c;
;         if (L < 256) {
;             const int xcd = (int)L % NXCD, off = (int)L / NXCD;
;             u.pm = xcd * 4 + (off & 3); u.pn = off >> 2; u.k0 = 0; u.nk = nkf; u.part = -1; return true;
;         }
;         const long p = L - 256 - poff; if (p < 0 || p >= 8 * nsl) return false;
;         const int sl = (int)p / 8, pairs = nkf / 2, base = pairs / nsl, rem = pairs % nsl;
;         u.pm = 32; u.pn = (int)p % 8; u.k0 = 2 * (sl * base + (sl < rem ? sl : rem)); u.nk = 2 * (base + (sl < rem ? 1 : 0)); u.part = sl; return true;
.LBB0_980:
	s_sub_u32 s0, s2, s15
	s_subb_u32 s1, 0, 0
	v_cmp_gt_u64_e64 s[22:23], s[0:1], 63
	s_and_b64 vcc, exec, s[22:23]
	s_cbranch_vccnz .LBB0_982
	s_and_b32 s1, s0, 7
	s_lshl_b32 s18, s1, 8
	s_lshr_b32 s44, s0, 3
	s_mov_b32 s67, 2
	s_mov_b32 s0, 32
	s_mov_b64 s[24:25], s[18:19]
	s_mov_b32 s18, s1
	s_xor_b64 s[22:23], s[28:29], -1
	s_branch .LBB0_927

;     __host__ __device__ bool next(int i, Unit& u) const {
;         const long L = (long)i * G + c;
;         if (L < 256) {
;             const int xcd = (int)L % NXCD, off = (int)L / NXCD;
;             u.pm = xcd * 4 + (off & 3); u.pn = off >> 2; u.k0 = 0; u.nk = nkf; u.part = -1; return true;
;         }
;         const long p = L - 256 - poff; if (p < 0 || p >= 8 * nsl) return false;
;         const int sl = (int)p / 8, pairs = nkf / 2, base = pairs / nsl, rem = pairs % nsl;
;         u.pm = 32; u.pn = (int)p % 8; u.k0 = 2 * (sl * base + (sl < rem ? sl : rem)); u.nk = 2 * (base + (sl < rem ? 1 : 0)); u.part = sl; return true;
.LBB0_1095:
	s_cmp_lt_i32 s66, 9
	s_cselect_b64 s[6:7], -1, 0
	s_and_b64 s[0:1], s[6:7], s[0:1]
	s_andn2_b64 vcc, exec, s[0:1]
	s_cbranch_vccnz .LBB0_1140
	s_cmpk_gt_i32 s33, 0xff
	v_readfirstlane_b32 s22, v203
	s_cbranch_scc0 .LBB0_1099
	s_add_i32 s2, s33, 0xffffff00
	s_cmpk_gt_u32 s2, 0x7f
	s_mov_b64 s[20:21], 0
	s_cbranch_scc1 .LBB0_1152
	s_and_b32 s16, s2, 15
	s_lshl_b32 s6, s16, 8
	s_mov_b32 s7, 0
	s_lshr_b32 s40, s2, 4
	s_mov_b32 s56, 2
	s_mov_b32 s38, 32
	s_mov_b64 s[18:19], -1
	s_andn2_b64 vcc, exec, s[20:21]
	s_cbranch_vccz .LBB0_1100
	s_branch .LBB0_1101

;     __host__ __device__ bool next(int i, Unit& u) const {
;         const long L = (long)i * G + c;
;         if (L < 256) {
;             const int xcd = (int)L % NXCD, off = (int)L / NXCD;
;             u.pm = xcd * 4 + (off & 3); u.pn = off >> 2; u.k0 = 0; u.nk = nkf; u.part = -1; return true;
;         }
;         const long p = L - 256 - poff; if (p < 0 || p >= 8 * nsl) return false;
;         const int sl = (int)p / 8, pairs = nkf / 2, base = pairs / nsl, rem = pairs % nsl;
;         u.pm = 32; u.pn = (int)p % 8; u.k0 = 2 * (sl * base + (sl < rem ? sl : rem)); u.nk = 2 * (base + (sl < rem ? 1 : 0)); u.part = sl; return true;
.LBB0_1107:
	s_add_i32 s53, s53, 1
	s_mul_i32 s25, s53, s50
	s_mul_hi_u32 s27, s53, s3
	s_add_i32 s27, s27, s25
	s_mul_i32 s25, s53, s3
	s_add_u32 s34, s25, s33
	s_addc_u32 s35, s27, s11
	v_cmp_gt_i64_e32 vcc, s[34:35], v[132:133]
	s_mov_b64 s[36:37], -1
	s_cbranch_vccz .LBB0_1110
	s_add_u32 s46, s34, 0xffffff00
	s_addc_u32 s47, s35, -1
	v_cmp_gt_u64_e32 vcc, s[46:47], v[134:135]
	s_mov_b64 s[36:37], 0
	s_mov_b64 s[30:31], 0
	s_cbranch_vccnz .LBB0_1110
	s_and_b32 s54, s46, 15
	s_lshl_b32 s24, s54, 1
	s_lshr_b32 s26, s46, 4
	s_mov_b32 s55, 2
	s_mov_b32 s28, 32
	s_mov_b64 s[30:31], -1

;     __host__ __device__ bool next(int i, Unit& u) const {
;         const long L = (long)i * G + c;
;         if (L < 256) {
;             const int xcd = (int)L % NXCD, off = (int)L / NXCD;
;             u.pm = xcd * 4 + (off & 3); u.pn = off >> 2; u.k0 = 0; u.nk = nkf; u.part = -1; return true;
;         }
;         const long p = L - 256 - poff; if (p < 0 || p >= 8 * nsl) return false;
;         const int sl = (int)p / 8, pairs = nkf / 2, base = pairs / nsl, rem = pairs % nsl;
;         u.pm = 32; u.pn = (int)p % 8; u.k0 = 2 * (sl * base + (sl < rem ? sl : rem)); u.nk = 2 * (base + (sl < rem ? 1 : 0)); u.part = sl; return true;
.LBB0_1400:
	s_cmp_lt_i32 s66, 12
	s_cselect_b64 s[8:9], -1, 0
	s_and_b64 s[12:13], s[8:9], s[0:1]
	s_add_u32 s8, s86, 0x4000000
	s_addc_u32 s9, s87, 0
	s_andn2_b64 vcc, exec, s[12:13]
	s_cbranch_vccnz .LBB0_1498
	s_cmpk_lt_i32 s33, 0x100
	v_readfirstlane_b32 s20, v203
	s_cbranch_scc1 .LBB0_1404
	s_add_i32 s1, s33, 0xffffff00
	s_cmpk_gt_u32 s1, 0xff
	s_cbranch_scc1 .LBB0_1405
	s_and_b32 s16, s1, 31
	s_min_u32 s0, s16, 11
	s_add_i32 s0, s0, s16
	s_lshr_b32 s75, s1, 5
	s_lshl_b32 s0, s0, 16
	s_cmpk_lt_u32 s16, 11
	s_cselect_b32 s76, 4, 2
	s_mov_b32 s1, 0
	s_mov_b32 s74, 32
	s_branch .LBB0_1406

;     __host__ __device__ bool next(int i, Unit& u) const {
;         const long L = (long)i * G + c;
;         if (L < 256) {
;             const int xcd = (int)L % NXCD, off = (int)L / NXCD;
;             u.pm = xcd * 4 + (off & 3); u.pn = off >> 2; u.k0 = 0; u.nk = nkf; u.part = -1; return true;
;         }
;         const long p = L - 256 - poff; if (p < 0 || p >= 8 * nsl) return false;
;         const int sl = (int)p / 8, pairs = nkf / 2, base = pairs / nsl, rem = pairs % nsl;
;         u.pm = 32; u.pn = (int)p % 8; u.k0 = 2 * (sl * base + (sl < rem ? sl : rem)); u.nk = 2 * (base + (sl < rem ? 1 : 0)); u.part = sl; return true;
.LBB0_1411:
	s_add_i32 s69, s69, 1
	s_mul_i32 s0, s69, s49
	s_mul_hi_u32 s1, s69, s3
	s_add_i32 s1, s1, s0
	s_mul_i32 s0, s69, s3
	s_add_u32 s0, s0, s33
	s_addc_u32 s1, s1, s11
	v_cmp_gt_i64_e32 vcc, s[0:1], v[138:139]
	s_mov_b64 s[38:39], -1
	s_cbranch_vccz .LBB0_1414
	s_add_u32 s44, s0, 0xffffff00
	s_addc_u32 s45, s1, -1
	v_cmp_gt_u64_e32 vcc, s[44:45], v[138:139]
	s_mov_b64 s[38:39], 0
	s_mov_b64 s[36:37], 0
	s_cbranch_vccnz .LBB0_1414
	s_and_b32 s70, s44, 31
	s_min_u32 s1, s70, 11
	s_add_i32 s1, s1, s70
	s_lshr_b32 s71, s44, 5
	v_cmp_lt_u64_e32 vcc, s[44:45], v[140:141]
	s_lshl_b32 s34, s1, 1
	s_cmp_lt_u32 s70, 11
	s_cselect_b32 s72, 4, 2
	s_mov_b32 s73, 32
	s_mov_b64 s[36:37], -1
